# phase 3 queue: per-XCD item queues with stealing; the diff-attention items of one (b,h) run together on one XCD ((b,h)-major order) so their K/V tiles are shared through that XCD's L2
# baseline (speedup 1.0000x reference)
.LBB0_1056:
	v_mov_b32_e32 v0, v230
	s_barrier
	s_nop 0
	v_cmp_eq_u32_e32 vcc, 0, v0
	s_and_saveexec_b64 s[0:1], vcc
	s_cbranch_execz .LBB0_1060
	v_readlane_b32 s26, v253, 18
	s_and_b32 s26, s26, 7
	s_mov_b32 s99, s26
.Lq3_pop:
	s_lshl_b32 s10, s99, 2
	v_mov_b32_e32 v0, s10
	v_mov_b32_e32 v1, 1
	global_atomic_add v1, v0, v1, s[44:45] offset:-68 sc0
	s_waitcnt vmcnt(0)
	v_readfirstlane_b32 s10, v1
	s_cmpk_lt_u32 s10, 0xa8
	s_cbranch_scc1 .Lq3_map
	s_mov_b64 exec, 0xff
	v_mbcnt_lo_u32_b32 v0, -1, 0
	v_lshlrev_b32_e32 v0, 2, v0
	global_load_dword v1, v0, s[44:45] offset:-68 sc1
	s_movk_i32 s10, 0xa8
	s_waitcnt vmcnt(0)
	v_cmp_gt_u32_e64 s[100:101], s10, v1
	s_mov_b64 exec, 1
	s_nop 3
	s_and_b32 s100, s100, 0xff
	s_cmp_eq_u32 s100, 0
	s_cbranch_scc1 .Lq3_none
	s_add_i32 s98, s26, 1
	s_lshr_b32 s101, s100, s98
	s_sub_i32 s10, 8, s98
	s_lshl_b32 s10, s100, s10
	s_or_b32 s101, s101, s10
	s_and_b32 s101, s101, 0xff
	s_ff1_i32_b32 s101, s101
	s_add_i32 s99, s98, s101
	s_and_b32 s99, s99, 7
	s_branch .Lq3_pop
.Lq3_none:
	s_movk_i32 s10, 0x540
	s_branch .Lq3_done
.Lq3_map:
	s_cmp_lt_u32 s10, 8
	s_cbranch_scc0 .Lq3_m1
	s_lshl_b32 s11, s99, 3
	s_add_i32 s10, s10, s11
	s_branch .Lq3_done
.Lq3_m1:
	s_cmpk_lt_u32 s10, 0x88
	s_cbranch_scc0 .Lq3_m2
	s_add_i32 s10, s10, -8
	s_and_b32 s11, s10, 31
	s_lshl_b32 s11, s11, 5
	s_lshr_b32 s10, s10, 5
	s_add_i32 s10, s10, s11
	s_lshl_b32 s11, s99, 2
	s_add_i32 s10, s10, s11
	s_add_i32 s10, s10, 64
	s_branch .Lq3_done
.Lq3_m2:
	s_lshl_b32 s11, s99, 5
	s_add_i32 s10, s10, s11
	s_addk_i32 s10, 0x3b8
.Lq3_done:
	v_mov_b32_e32 v0, s10
	v_mov_b32_e32 v1, s13
	ds_write_b32 v1, v0
